# v101 without the redundant counted wait in P1 first K-iteration (previous unit's last vmcnt(4) already guarantees tile completion)
# speedup vs baseline: 1.0031x; 1.0021x over previous
.LBB0_381:
.LBB0_383:
	s_add_u32 s39, s82, 0x100
	s_addc_u32 s67, s83, 0
	s_mov_b32 s94, -2
	s_mov_b64 vcc, 0
	v_lshl_add_u64 v[132:133], s[4:5], 0, v[168:169]
	ds_read_b128 v[134:137], v199
	ds_read_b128 v[138:141], v200
	ds_read_b128 v[142:145], v201
	ds_read_b128 v[146:149], v202
	ds_read_b128 v[150:153], v203
	ds_read_b128 v[174:177], v204
	ds_read_b128 v[178:181], v205
	ds_read_b128 v[182:185], v206
	s_add_u32 s24, s4, vcc_lo
	s_addc_u32 s25, s5, vcc_hi
	s_add_u32 s24, s24, 0x100
	s_addc_u32 s25, s25, 0
	s_add_u32 s82, s39, vcc_lo
	s_addc_u32 s83, s67, vcc_hi
	s_cmpk_eq_i32 vcc_lo, 0x700
	s_cselect_b32 s87, s29, s83
	s_cselect_b32 s86, s38, s82
	s_cselect_b32 s83, s34, s25
	s_cselect_b32 s82, s35, s24
	v_lshl_add_u64 v[154:155], v[132:133], 0, vcc
	v_lshl_add_u64 v[250:251], v[154:155], 0, s[48:49]
	s_add_i32 m0, s79, 0x8000
	s_mov_b64 s[24:25], 0x20080
	ds_read_b128 v[218:221], v207
	ds_read_b128 v[222:225], v207 offset:2048
	ds_read_b128 v[226:229], v208
	ds_read_b128 v[230:233], v208 offset:2048
	ds_read_b128 v[234:237], v207 offset:4096
	ds_read_b128 v[238:241], v207 offset:6144
	ds_read_b128 v[242:245], v208 offset:4096
	ds_read_b128 v[246:249], v208 offset:6144
	global_load_lds_dwordx4 v[250:251], off
	v_lshl_add_u64 v[250:251], v[154:155], 0, s[24:25]
	s_add_i32 m0, s79, 0xa000
	s_mov_b64 s[24:25], 0x60080
	global_load_lds_dwordx4 v[250:251], off
	v_lshl_add_u64 v[250:251], v[154:155], 0, s[50:51]
	s_add_i32 m0, s79, 0xc000
	v_lshl_add_u64 v[154:155], v[154:155], 0, s[24:25]
	global_load_lds_dwordx4 v[250:251], off
	s_add_i32 m0, s79, 0xe000
	s_nop 0
	global_load_lds_dwordx4 v[154:155], off
	s_waitcnt lgkmcnt(0)
	s_barrier
	s_setprio 0
	s_cmp_lg_u32 s98, 0
	s_cbranch_scc1 .Lp1b_skip
	v_mbcnt_lo_u32_b32 v255, -1, 0
	v_mbcnt_hi_u32_b32 v255, -1, v255
	s_cmp_gt_i32 s96, 13
	s_cbranch_scc1 .Lp1b_gate
	s_lshl_b32 s100, s96, 10
	s_add_u32 s100, s90, s100
	s_addc_u32 s101, s91, 0
	v_lshlrev_b32_e32 v255, 4, v255
	s_branch .Lp1b_issue
